# defer non-w_in weight transposes from P0 to the idle 192 CUs in P1's 17th round
# speedup vs baseline: 1.0197x; 1.0136x over previous
; #define LAS __attribute__((address_space(3)))
; __device__ __forceinline__ int fresh_tid(int wave_s) { unsigned m = ~0u; asm volatile("" : "+s"(m)); int t = wave_s * 64 + (int)__builtin_amdgcn_mbcnt_hi(m, __builtin_amdgcn_mbcnt_lo(m, 0u)); asm volatile("" : "+v"(t)); return t; }
; __device__ __forceinline__ void p0_prep(const Ctx& c, LAS unsigned char* lds, int vcu, int G, int wave_s) {
;     const int tid_ = fresh_tid(wave_s); const int lane = tid_ & 63, wave = __builtin_amdgcn_readfirstlane(tid_ >> 6);
;     unsigned char* ws = c.ws;
;     LAS float* scr = (LAS float*)(lds + wave * 16384);
;     const int gw = vcu * 8 + wave, NGW = G * 8;
;     constexpr int I_IN = (D / 64) * (8192 / 32), I_SQ = (D / 64) * (D / 32), I_UP = (D / 64) * (2 * DFF / 32), I_DN = (DFF / 64) * (D / 32);
;     constexpr int NITEMS = I_IN + 3 * I_SQ + I_UP + I_DN;
;     for (int it = gw; it < NITEMS; it += NGW) {
;         int r = it;
;         if (r < I_IN) { transpose_item<1>(c.w_in, D, 8192, (bf16*)(ws + WS_WIN), scr, r, lane, nullptr); continue; } r -= I_IN;
.LBB0_7:
	s_or_b64 exec, exec, s[2:3]
	s_mov_b32 s98, 0
	s_movk_i32 s99, 0xfff
	s_load_dwordx16 s[36:51], s[0:1], 0x0
	s_load_dwordx16 s[16:31], s[0:1], 0x40
	s_mov_b32 s0, -1
	s_lshl_b32 s70, s15, 3
	v_mbcnt_lo_u32_b32 v2, s0, 0
	v_mbcnt_hi_u32_b32 v2, s0, v2
	v_add_u32_e32 v3, s33, v2
	s_mov_b32 s1, 0
	v_readfirstlane_b32 s0, v3
	s_ashr_i32 s13, s0, 6
	s_lshl_b32 s0, s57, 3
	s_add_i32 s12, s13, s0
	v_writelane_b32 v255, s0, 2
	s_cmpk_gt_i32 s12, 0xfff
	v_and_b32_e32 v2, 63, v3
	s_cbranch_scc1 .LBB0_30
	v_and_b32_e32 v28, 7, v3
	s_lshl_b32 s0, s13, 14
	v_lshlrev_b32_e32 v4, 4, v28
	v_mov_b32_e32 v5, 0
	s_add_i32 s0, s0, 0
	v_lshrrev_b32_e32 v18, 3, v2
	v_lshl_add_u64 v[16:17], s[34:35], 0, v[4:5]
	s_mov_b64 s[2:3], 0x2200000
	v_add_u32_e32 v29, s0, v4
	v_mul_u32_u24_e32 v8, 0x420, v28
	v_lshl_add_u64 v[6:7], v[16:17], 0, s[2:3]
	v_lshlrev_b32_e32 v4, 2, v18
	s_mov_b64 s[2:3], 0x1700000
	v_add3_u32 v27, s0, v8, v4
	v_lshl_add_u64 v[8:9], v[16:17], 0, s[2:3]
	s_mov_b64 s[2:3], 0x1500000
	v_lshl_add_u64 v[10:11], v[16:17], 0, s[2:3]
	s_mov_b64 s[2:3], 0x1300000
	v_mul_u32_u24_e32 v30, 0x84, v18
	v_lshl_add_u64 v[12:13], v[16:17], 0, s[2:3]
	s_mov_b64 s[2:3], 0x1100000
	v_lshl_add_u64 v[14:15], v[16:17], 0, s[2:3]
	s_mov_b64 s[2:3], 0x100000
	v_lshlrev_b32_e32 v4, 6, v28
	s_lshl_b32 s0, s12, 1
	v_add_u32_e32 v29, v29, v30
	v_lshlrev_b32_e32 v19, 2, v28
	v_or_b32_e32 v20, 8, v18
	v_or_b32_e32 v21, 16, v18
	v_or_b32_e32 v22, 24, v18
	v_or_b32_e32 v23, 32, v18
	v_or_b32_e32 v24, 40, v18
	v_or_b32_e32 v25, 48, v18
	v_or_b32_e32 v26, 56, v18
	v_lshl_add_u64 v[16:17], v[16:17], 0, s[2:3]
	s_lshl_b32 s58, s12, 5
	s_lshl_b32 s59, s70, 5
	v_lshl_or_b32 v28, s12, 9, v4
	s_lshl_b32 s60, s70, 9
	s_add_i32 s61, s0, 0xffffbe00
	s_lshl_b32 s62, s70, 1
	v_add_u32_e32 v30, 0x420, v29
	v_add_u32_e32 v31, 0x428, v29
	v_add_u32_e32 v32, 0x840, v29
	v_add_u32_e32 v33, 0x848, v29
	v_add_u32_e32 v34, 0xc60, v29
	v_add_u32_e32 v35, 0xc68, v29
	v_add_u32_e32 v36, 0x1080, v29
	v_add_u32_e32 v37, 0x1088, v29
	v_add_u32_e32 v38, 0x14a0, v29
	v_add_u32_e32 v39, 0x14a8, v29
	v_add_u32_e32 v40, 0x18c0, v29
	v_add_u32_e32 v41, 0x18c8, v29
	v_add_u32_e32 v42, 0x1ce0, v29
	v_add_u32_e32 v43, 0x1ce8, v29
	s_movk_i32 s63, 0x5800
	s_movk_i32 s64, 0x3ff
	s_mov_b32 s65, s12
	s_branch .LBB0_10
.LBB0_9:
	s_add_i32 s65, s65, s70
	s_add_i32 s58, s58, s59
	s_add_i32 s61, s61, s62
	s_cmp_gt_i32 s65, s99
	v_add_u32_e32 v28, s60, v28
	s_cbranch_scc1 .Lp0_items_done

; __device__ __forceinline__ void p0_prep(const Ctx& c, LAS unsigned char* lds, int vcu, int G, int wave_s) {
;     ...
;     for (int it = gw; it < NITEMS; it += NGW) {
;         int r = it;
;         if (r < I_IN) { transpose_item<1>(c.w_in, D, 8192, (bf16*)(ws + WS_WIN), scr, r, lane, nullptr); continue; } r -= I_IN;
;         if (r < I_SQ) { transpose_item<0>(c.w_rb, D, D, (bf16*)(ws + WS_WRB), scr, r, lane, nullptr); continue; } r -= I_SQ;
;         if (r < I_SQ) { transpose_item<0>(c.w_db, D, D, (bf16*)(ws + WS_WDB), scr, r, lane, nullptr); continue; } r -= I_SQ;
;         if (r < I_SQ) { transpose_item<0>(c.w_o, D, D, (bf16*)(ws + WS_WO), scr, r, lane, nullptr); continue; } r -= I_SQ;
;         if (r < I_UP) { transpose_item<2>(c.w_up, D, 2 * DFF, (bf16*)(ws + WS_WUP), scr, r, lane, c.n2g); continue; } r -= I_UP;
;         transpose_item<0>(c.w_down, DFF, D, (bf16*)(ws + WS_WDN), scr, r, lane, nullptr);
;     }
.Lp0_items_done:
	s_cmp_eq_u32 s98, 0
	s_cbranch_scc0 .Lp0b_done

; __device__ __forceinline__ void p0_prep(const Ctx& c, LAS unsigned char* lds, int vcu, int G, int wave_s) {
;     ...
;     constexpr int I_IN = (D / 64) * (8192 / 32), I_SQ = (D / 64) * (D / 32), I_UP = (D / 64) * (2 * DFF / 32), I_DN = (DFF / 64) * (D / 32);
;     constexpr int NITEMS = I_IN + 3 * I_SQ + I_UP + I_DN;
;     for (int it = gw; it < NITEMS; it += NGW) {
;         int r = it;
;         if (r < I_IN) { transpose_item<1>(c.w_in, D, 8192, (bf16*)(ws + WS_WIN), scr, r, lane, nullptr); continue; } r -= I_IN;
;         if (r < I_SQ) { transpose_item<0>(c.w_rb, D, D, (bf16*)(ws + WS_WRB), scr, r, lane, nullptr); continue; } r -= I_SQ;
;         if (r < I_SQ) { transpose_item<0>(c.w_db, D, D, (bf16*)(ws + WS_WDB), scr, r, lane, nullptr); continue; } r -= I_SQ;
;         if (r < I_SQ) { transpose_item<0>(c.w_o, D, D, (bf16*)(ws + WS_WO), scr, r, lane, nullptr); continue; } r -= I_SQ;
;         if (r < I_UP) { transpose_item<2>(c.w_up, D, 2 * DFF, (bf16*)(ws + WS_WUP), scr, r, lane, c.n2g); continue; } r -= I_UP;
;         transpose_item<0>(c.w_down, DFF, D, (bf16*)(ws + WS_WDN), scr, r, lane, nullptr);
;     }
; __global__ void __launch_bounds__(512, 2) hybrid_fwd(Ctx c) {
;     ...
;     { pg8::Gemm g{(const pg8::bf16_t*)(ws + WS_XN), (const pg8::bf16_t*)(ws + WS_WIN), R_ALL, 8192, D}; pg8::StaticOrder S; S.init(R_ALL, 8192, G, bx);
;       EpiIn E{c}; pg8::gemm_phase<EpiIn, pg8::StaticOrder, true, true>(lds, g, S, E, wave0); }
.LBB0_603:
	v_readlane_b32 s0, v255, 2
	s_bfe_u32 s1, s0, 0x50003
	s_cmp_lt_u32 s1, 8
	s_cbranch_scc1 .Lp0b_skip
	v_writelane_b32 v250, s2, 0
	v_writelane_b32 v250, s3, 1
	v_writelane_b32 v250, s4, 2
	v_writelane_b32 v250, s5, 3
	v_writelane_b32 v250, s6, 4
	v_writelane_b32 v250, s7, 5
	v_writelane_b32 v250, s8, 6
	v_writelane_b32 v250, s9, 7
	v_writelane_b32 v250, s10, 8
	v_writelane_b32 v250, s11, 9
	v_writelane_b32 v250, s12, 10
	v_writelane_b32 v250, s13, 11
	v_writelane_b32 v250, s14, 12
	v_writelane_b32 v250, s15, 13
	v_writelane_b32 v250, s16, 14
	v_writelane_b32 v250, s17, 15
	v_writelane_b32 v250, s18, 16
	v_writelane_b32 v250, s19, 17
	v_writelane_b32 v250, s20, 18
	v_writelane_b32 v250, s21, 19
	v_writelane_b32 v250, s22, 20
	v_writelane_b32 v250, s23, 21
	v_writelane_b32 v250, s24, 22
	v_writelane_b32 v250, s25, 23
	v_writelane_b32 v250, s26, 24
	v_writelane_b32 v250, s27, 25
	v_writelane_b32 v250, s28, 26
	v_writelane_b32 v250, s29, 27
	v_writelane_b32 v250, s30, 28
	v_writelane_b32 v250, s31, 29
	v_writelane_b32 v250, s58, 30
	v_writelane_b32 v250, s59, 31
	v_writelane_b32 v250, s60, 32
	v_writelane_b32 v250, s61, 33
	v_writelane_b32 v250, s62, 34
	v_writelane_b32 v250, s63, 35
	v_writelane_b32 v250, s64, 36
	v_writelane_b32 v250, s65, 37
	v_writelane_b32 v250, s66, 38
	v_writelane_b32 v250, s67, 39
	v_writelane_b32 v250, s68, 40
	v_writelane_b32 v250, s69, 41
	v_writelane_b32 v250, s70, 42
	v_writelane_b32 v250, vcc_lo, 43
	v_writelane_b32 v250, vcc_hi, 44
	v_readlane_b32 s0, v255, 0
	v_readlane_b32 s1, v255, 1
	s_sub_u32 s0, s0, 0xb8
	s_subb_u32 s1, s1, 0
	s_load_dwordx8 s[4:11], s[0:1], 0x80
	s_load_dwordx16 s[16:31], s[0:1], 0x40
	v_readlane_b32 s2, v255, 2
	s_lshr_b32 s2, s2, 3
	s_lshr_b32 s3, s2, 5
	s_and_b32 s2, s2, 31
	s_mul_i32 s3, s3, 24
	s_add_i32 s2, s2, s3
	s_add_i32 s2, s2, -8
	s_lshl_b32 s2, s2, 3
	s_addk_i32 s2, 0x1000
	s_mov_b32 s98, 1
	s_movk_i32 s99, 0x267f
	s_movk_i32 s70, 0x600
	s_mov_b32 s0, -1
	v_mbcnt_lo_u32_b32 v2, s0, 0
	v_mbcnt_hi_u32_b32 v2, s0, v2
	v_add_u32_e32 v3, s33, v2
	s_mov_b32 s1, 0
	v_readfirstlane_b32 s0, v3
	s_ashr_i32 s13, s0, 6
	s_add_i32 s12, s13, s2
	s_cmp_gt_i32 s12, s99
	v_and_b32_e32 v2, 63, v3
	s_cbranch_scc1 .Lp0b_done
	v_and_b32_e32 v28, 7, v3
	s_lshl_b32 s0, s13, 14
	v_lshlrev_b32_e32 v4, 4, v28
	v_mov_b32_e32 v5, 0
	s_add_i32 s0, s0, 0
	v_lshrrev_b32_e32 v18, 3, v2
	v_lshl_add_u64 v[16:17], s[34:35], 0, v[4:5]
	s_mov_b64 s[2:3], 0x2200000
	v_add_u32_e32 v29, s0, v4
	v_mul_u32_u24_e32 v8, 0x420, v28
	v_lshl_add_u64 v[6:7], v[16:17], 0, s[2:3]
	v_lshlrev_b32_e32 v4, 2, v18
	s_mov_b64 s[2:3], 0x1700000
	v_add3_u32 v27, s0, v8, v4
	v_lshl_add_u64 v[8:9], v[16:17], 0, s[2:3]
	s_mov_b64 s[2:3], 0x1500000
	v_lshl_add_u64 v[10:11], v[16:17], 0, s[2:3]
	s_mov_b64 s[2:3], 0x1300000
	v_mul_u32_u24_e32 v30, 0x84, v18
	v_lshl_add_u64 v[12:13], v[16:17], 0, s[2:3]
	s_mov_b64 s[2:3], 0x1100000
	v_lshl_add_u64 v[14:15], v[16:17], 0, s[2:3]
	s_mov_b64 s[2:3], 0x100000
	v_lshlrev_b32_e32 v4, 6, v28
	s_lshl_b32 s0, s12, 1
	v_add_u32_e32 v29, v29, v30
	v_lshlrev_b32_e32 v19, 2, v28
	v_or_b32_e32 v20, 8, v18
	v_or_b32_e32 v21, 16, v18
	v_or_b32_e32 v22, 24, v18
	v_or_b32_e32 v23, 32, v18
	v_or_b32_e32 v24, 40, v18
	v_or_b32_e32 v25, 48, v18
	v_or_b32_e32 v26, 56, v18
	v_lshl_add_u64 v[16:17], v[16:17], 0, s[2:3]
	s_lshl_b32 s58, s12, 5
	s_lshl_b32 s59, s70, 5
	v_lshl_or_b32 v28, s12, 9, v4
	s_lshl_b32 s60, s70, 9
	s_add_i32 s61, s0, 0xffffbe00
	s_lshl_b32 s62, s70, 1
	v_add_u32_e32 v30, 0x420, v29
	v_add_u32_e32 v31, 0x428, v29
	v_add_u32_e32 v32, 0x840, v29
	v_add_u32_e32 v33, 0x848, v29
	v_add_u32_e32 v34, 0xc60, v29
	v_add_u32_e32 v35, 0xc68, v29
	v_add_u32_e32 v36, 0x1080, v29
	v_add_u32_e32 v37, 0x1088, v29
	v_add_u32_e32 v38, 0x14a0, v29
	v_add_u32_e32 v39, 0x14a8, v29
	v_add_u32_e32 v40, 0x18c0, v29
	v_add_u32_e32 v41, 0x18c8, v29
	v_add_u32_e32 v42, 0x1ce0, v29
	v_add_u32_e32 v43, 0x1ce8, v29
	s_movk_i32 s63, 0x5800
	s_movk_i32 s64, 0x3ff
	s_mov_b32 s65, s12
	s_waitcnt lgkmcnt(0)
	s_branch .LBB0_10
.Lp0b_done:
	v_readlane_b32 s2, v250, 0
	v_readlane_b32 s3, v250, 1
	v_readlane_b32 s4, v250, 2
	v_readlane_b32 s5, v250, 3
	v_readlane_b32 s6, v250, 4
	v_readlane_b32 s7, v250, 5
	v_readlane_b32 s8, v250, 6
	v_readlane_b32 s9, v250, 7
	v_readlane_b32 s10, v250, 8
	v_readlane_b32 s11, v250, 9
	v_readlane_b32 s12, v250, 10
	v_readlane_b32 s13, v250, 11
	v_readlane_b32 s14, v250, 12
	v_readlane_b32 s15, v250, 13
	v_readlane_b32 s16, v250, 14
	v_readlane_b32 s17, v250, 15
	v_readlane_b32 s18, v250, 16
	v_readlane_b32 s19, v250, 17
	v_readlane_b32 s20, v250, 18
	v_readlane_b32 s21, v250, 19
	v_readlane_b32 s22, v250, 20
	v_readlane_b32 s23, v250, 21
	v_readlane_b32 s24, v250, 22
	v_readlane_b32 s25, v250, 23
	v_readlane_b32 s26, v250, 24
	v_readlane_b32 s27, v250, 25
	v_readlane_b32 s28, v250, 26
	v_readlane_b32 s29, v250, 27
	v_readlane_b32 s30, v250, 28
	v_readlane_b32 s31, v250, 29
	v_readlane_b32 s58, v250, 30
	v_readlane_b32 s59, v250, 31
	v_readlane_b32 s60, v250, 32
	v_readlane_b32 s61, v250, 33
	v_readlane_b32 s62, v250, 34
	v_readlane_b32 s63, v250, 35
	v_readlane_b32 s64, v250, 36
	v_readlane_b32 s65, v250, 37
	v_readlane_b32 s66, v250, 38
	v_readlane_b32 s67, v250, 39
	v_readlane_b32 s68, v250, 40
	v_readlane_b32 s69, v250, 41
	v_readlane_b32 s70, v250, 42
	v_readlane_b32 vcc_lo, v250, 43
	v_readlane_b32 vcc_hi, v250, 44
	s_nop 4
